# stacked small edits: single wait for the V fragments in attention, 64-bit accumulator zeroing in the up-GEMM unit loop, first conv half reads boundary rows before weights with a counted wait
# speedup vs baseline: 1.0085x; 1.0063x over previous
; __device__ __forceinline__ unsigned cvtpk(float lo, float hi) { const f32x2 v = {lo, hi}; const bf16x2_t b = __builtin_convertvector(v, bf16x2_t); return __builtin_bit_cast(unsigned, b); }
; __device__ __forceinline__ void sm_pv(f32x16& s0, f32x16& s1, f32x16& o0, f32x16& o1, float& m_run, float& l_run, f32x16& negm, LAS unsigned char* vb, bool domask, int kbase, int qm, int r32, int hi) {
;     ...
;     f32x2 ps2 = (f32x2){0.f, 0.f};
; #pragma unroll
;     for (int r = 0; r < 16; r += 2) { s0[r] = __builtin_amdgcn_exp2f(s0[r]); s0[r + 1] = __builtin_amdgcn_exp2f(s0[r + 1]); s1[r] = __builtin_amdgcn_exp2f(s1[r]); s1[r + 1] = __builtin_amdgcn_exp2f(s1[r + 1]);
;         ps2 += (f32x2){s0[r], s0[r + 1]}; ps2 += (f32x2){s1[r], s1[r + 1]}; }
;     l_run += ps2[0] + ps2[1];
;     u32x4 pw[4];
; #pragma unroll
;     for (int i = 0; i < 4; ++i) { pw[0][i] = cvtpk(s0[2 * i], s0[2 * i + 1]); pw[1][i] = cvtpk(s0[8 + 2 * i], s0[8 + 2 * i + 1]); pw[2][i] = cvtpk(s1[2 * i], s1[2 * i + 1]); pw[3][i] = cvtpk(s1[8 + 2 * i], s1[8 + 2 * i + 1]); }
; #pragma unroll
;     for (int kk = 0; kk < 4; ++kk) {
;         const bf16x8 pf = __builtin_bit_cast(bf16x8, pw[kk]);
;         { const s16x4 lo = vlo[2 * kk], hh = vhh[2 * kk];
;           const bf16x8 vf = (bf16x8){lo[0], lo[1], lo[2], lo[3], hh[0], hh[1], hh[2], hh[3]};
;           o0 = __builtin_amdgcn_mfma_f32_32x32x16_bf16(vf, pf, o0, 0, 0, 0); }
;         { const s16x4 lo = vlo[2 * kk + 1], hh = vhh[2 * kk + 1];
;           const bf16x8 vf = (bf16x8){lo[0], lo[1], lo[2], lo[3], hh[0], hh[1], hh[2], hh[3]};
;           o1 = __builtin_amdgcn_mfma_f32_32x32x16_bf16(vf, pf, o1, 0, 0, 0); }
;     }
.LBB0_425:
	v_exp_f32_e32 v80, v80
	v_exp_f32_e32 v81, v81
	v_exp_f32_e32 v228, v82
	v_exp_f32_e32 v229, v83
	v_exp_f32_e32 v84, v84
	v_exp_f32_e32 v85, v85
	v_exp_f32_e32 v86, v86
	v_exp_f32_e32 v87, v87
	v_exp_f32_e32 v224, v64
	v_exp_f32_e32 v225, v65
	v_add_f32_e32 v64, 0, v80
	v_add_f32_e32 v65, 0, v81
	v_cvt_pk_bf16_f32 v80, v80, v81
	v_cvt_pk_bf16_f32 v81, v228, v229
	v_cvt_pk_bf16_f32 v82, v84, v85
	v_cvt_pk_bf16_f32 v83, v86, v87
	v_exp_f32_e32 v88, v88
	v_exp_f32_e32 v89, v89
	s_waitcnt lgkmcnt(0)
	v_mfma_f32_32x32x16_bf16 v[32:47], v[160:163], v[80:83], v[32:47]
	v_exp_f32_e32 v90, v90
	v_exp_f32_e32 v91, v91
	v_exp_f32_e32 v92, v92
	v_exp_f32_e32 v93, v93
	v_add_f32_e32 v226, v224, v64
	v_add_f32_e32 v227, v225, v65
	v_exp_f32_e32 v230, v66
	v_exp_f32_e32 v231, v67
	v_mfma_f32_32x32x16_bf16 v[16:31], v[156:159], v[80:83], v[16:31]
	v_exp_f32_e32 v80, v94
	v_exp_f32_e32 v81, v95
	v_cvt_pk_bf16_f32 v64, v88, v89
	v_cvt_pk_bf16_f32 v65, v90, v91
	v_cvt_pk_bf16_f32 v66, v92, v93
	v_cvt_pk_bf16_f32 v67, v80, v81
	v_exp_f32_e32 v68, v68
	v_exp_f32_e32 v69, v69
	v_mfma_f32_32x32x16_bf16 v[32:47], v[152:155], v[64:67], v[32:47]
	v_exp_f32_e32 v70, v70
	v_exp_f32_e32 v71, v71
	v_add_f32_e32 v82, v228, v226
	v_add_f32_e32 v83, v229, v227
	v_exp_f32_e32 v72, v72
	v_add_f32_e32 v82, v230, v82
	v_add_f32_e32 v83, v231, v83
	v_exp_f32_e32 v73, v73
	v_add_f32_e32 v82, v84, v82
	v_add_f32_e32 v83, v85, v83
	v_mfma_f32_32x32x16_bf16 v[16:31], v[148:151], v[64:67], v[16:31]
	v_cvt_pk_bf16_f32 v64, v224, v225
	v_cvt_pk_bf16_f32 v65, v230, v231
	v_cvt_pk_bf16_f32 v66, v68, v69
	v_cvt_pk_bf16_f32 v67, v70, v71
	v_add_f32_e64 v82, v68, v82
	v_add_f32_e64 v83, v69, v83
	v_add_f32_e32 v82, v86, v82
	v_add_f32_e32 v83, v87, v83
	v_mfma_f32_32x32x16_bf16 v[32:47], v[144:147], v[64:67], v[32:47]
	v_add_f32_e64 v68, v70, v82
	v_add_f32_e64 v69, v71, v83
	v_exp_f32_e32 v70, v74
	v_exp_f32_e32 v71, v75
	v_exp_f32_e32 v74, v76
	v_exp_f32_e32 v75, v77
	v_exp_f32_e32 v76, v78
	v_exp_f32_e32 v77, v79
	v_mfma_f32_32x32x16_bf16 v[16:31], v[140:143], v[64:67], v[16:31]
	v_add_f32_e64 v68, v88, v68
	v_add_f32_e64 v69, v89, v69
	v_cvt_pk_bf16_f32 v64, v72, v73
	v_add_f32_e64 v68, v72, v68
	v_add_f32_e64 v69, v73, v69
	v_cvt_pk_bf16_f32 v65, v70, v71
	v_cvt_pk_bf16_f32 v66, v74, v75
	v_cvt_pk_bf16_f32 v67, v76, v77
	v_add_f32_e32 v68, v90, v68
	v_add_f32_e32 v69, v91, v69
	v_mfma_f32_32x32x16_bf16 v[32:47], v[136:139], v[64:67], v[32:47]
	v_add_f32_e64 v68, v70, v68
	v_add_f32_e64 v69, v71, v69
	v_add_f32_e64 v68, v92, v68
	v_add_f32_e64 v69, v93, v69
	v_add_f32_e64 v68, v74, v68
	v_add_f32_e64 v69, v75, v69
	v_add_f32_e32 v68, v80, v68
	v_add_f32_e32 v69, v81, v69
	v_mfma_f32_32x32x16_bf16 v[16:31], v[10:13], v[64:67], v[16:31]
	v_add_f32_e64 v68, v76, v68
	v_add_f32_e64 v69, v77, v69
	v_add_f32_e32 v68, v68, v69
	v_add_f32_e32 v218, v218, v68

; __device__ __forceinline__ unsigned cvtpk(float lo, float hi) { const f32x2 v = {lo, hi}; const bf16x2_t b = __builtin_convertvector(v, bf16x2_t); return __builtin_bit_cast(unsigned, b); }
; __device__ __forceinline__ void sm_pv(f32x16& s0, f32x16& s1, f32x16& o0, f32x16& o1, float& m_run, float& l_run, f32x16& negm, LAS unsigned char* vb, bool domask, int kbase, int qm, int r32, int hi) {
;     ...
;     f32x2 ps2 = (f32x2){0.f, 0.f};
; #pragma unroll
;     for (int r = 0; r < 16; r += 2) { s0[r] = __builtin_amdgcn_exp2f(s0[r]); s0[r + 1] = __builtin_amdgcn_exp2f(s0[r + 1]); s1[r] = __builtin_amdgcn_exp2f(s1[r]); s1[r + 1] = __builtin_amdgcn_exp2f(s1[r + 1]);
;         ps2 += (f32x2){s0[r], s0[r + 1]}; ps2 += (f32x2){s1[r], s1[r + 1]}; }
;     l_run += ps2[0] + ps2[1];
;     u32x4 pw[4];
; #pragma unroll
;     for (int i = 0; i < 4; ++i) { pw[0][i] = cvtpk(s0[2 * i], s0[2 * i + 1]); pw[1][i] = cvtpk(s0[8 + 2 * i], s0[8 + 2 * i + 1]); pw[2][i] = cvtpk(s1[2 * i], s1[2 * i + 1]); pw[3][i] = cvtpk(s1[8 + 2 * i], s1[8 + 2 * i + 1]); }
; #pragma unroll
;     for (int kk = 0; kk < 4; ++kk) {
;         const bf16x8 pf = __builtin_bit_cast(bf16x8, pw[kk]);
;         { const s16x4 lo = vlo[2 * kk], hh = vhh[2 * kk];
;           const bf16x8 vf = (bf16x8){lo[0], lo[1], lo[2], lo[3], hh[0], hh[1], hh[2], hh[3]};
;           o0 = __builtin_amdgcn_mfma_f32_32x32x16_bf16(vf, pf, o0, 0, 0, 0); }
;         { const s16x4 lo = vlo[2 * kk + 1], hh = vhh[2 * kk + 1];
;           const bf16x8 vf = (bf16x8){lo[0], lo[1], lo[2], lo[3], hh[0], hh[1], hh[2], hh[3]};
;           o1 = __builtin_amdgcn_mfma_f32_32x32x16_bf16(vf, pf, o1, 0, 0, 0); }
;     }
.LBB0_436:
	v_exp_f32_e32 v80, v80
	v_exp_f32_e32 v81, v81
	v_exp_f32_e32 v226, v82
	v_exp_f32_e32 v227, v83
	v_exp_f32_e32 v84, v84
	v_exp_f32_e32 v85, v85
	v_exp_f32_e32 v86, v86
	v_exp_f32_e32 v87, v87
	v_exp_f32_e32 v222, v64
	v_exp_f32_e32 v223, v65
	v_add_f32_e32 v64, 0, v80
	v_add_f32_e32 v65, 0, v81
	v_cvt_pk_bf16_f32 v80, v80, v81
	v_cvt_pk_bf16_f32 v81, v226, v227
	v_cvt_pk_bf16_f32 v82, v84, v85
	v_cvt_pk_bf16_f32 v83, v86, v87
	v_exp_f32_e32 v88, v88
	v_exp_f32_e32 v89, v89
	s_waitcnt lgkmcnt(0)
	v_mfma_f32_32x32x16_bf16 v[32:47], v[160:163], v[80:83], v[32:47]
	v_exp_f32_e32 v90, v90
	v_exp_f32_e32 v91, v91
	v_exp_f32_e32 v92, v92
	v_exp_f32_e32 v93, v93
	v_add_f32_e32 v224, v222, v64
	v_add_f32_e32 v225, v223, v65
	v_exp_f32_e32 v228, v66
	v_exp_f32_e32 v229, v67
	v_mfma_f32_32x32x16_bf16 v[16:31], v[156:159], v[80:83], v[16:31]
	v_exp_f32_e32 v80, v94
	v_exp_f32_e32 v81, v95
	v_cvt_pk_bf16_f32 v64, v88, v89
	v_cvt_pk_bf16_f32 v65, v90, v91
	v_cvt_pk_bf16_f32 v66, v92, v93
	v_cvt_pk_bf16_f32 v67, v80, v81
	v_exp_f32_e32 v68, v68
	v_exp_f32_e32 v69, v69
	v_mfma_f32_32x32x16_bf16 v[32:47], v[152:155], v[64:67], v[32:47]
	v_exp_f32_e32 v70, v70
	v_exp_f32_e32 v71, v71
	v_add_f32_e32 v82, v226, v224
	v_add_f32_e32 v83, v227, v225
	v_exp_f32_e32 v72, v72
	v_add_f32_e32 v82, v228, v82
	v_add_f32_e32 v83, v229, v83
	v_exp_f32_e32 v73, v73
	v_add_f32_e32 v82, v84, v82
	v_add_f32_e32 v83, v85, v83
	v_mfma_f32_32x32x16_bf16 v[16:31], v[148:151], v[64:67], v[16:31]
	v_cvt_pk_bf16_f32 v64, v222, v223
	v_cvt_pk_bf16_f32 v65, v228, v229
	v_cvt_pk_bf16_f32 v66, v68, v69
	v_cvt_pk_bf16_f32 v67, v70, v71
	v_add_f32_e64 v82, v68, v82
	v_add_f32_e64 v83, v69, v83
	v_add_f32_e32 v82, v86, v82
	v_add_f32_e32 v83, v87, v83
	v_mfma_f32_32x32x16_bf16 v[32:47], v[144:147], v[64:67], v[32:47]
	v_add_f32_e64 v68, v70, v82
	v_add_f32_e64 v69, v71, v83
	v_exp_f32_e32 v70, v74
	v_exp_f32_e32 v71, v75
	v_exp_f32_e32 v74, v76
	v_exp_f32_e32 v75, v77
	v_exp_f32_e32 v76, v78
	v_exp_f32_e32 v77, v79
	v_mfma_f32_32x32x16_bf16 v[16:31], v[140:143], v[64:67], v[16:31]
	v_add_f32_e64 v68, v88, v68
	v_add_f32_e64 v69, v89, v69
	v_cvt_pk_bf16_f32 v64, v72, v73
	v_add_f32_e64 v68, v72, v68
	v_add_f32_e64 v69, v73, v69
	v_cvt_pk_bf16_f32 v65, v70, v71
	v_cvt_pk_bf16_f32 v66, v74, v75
	v_cvt_pk_bf16_f32 v67, v76, v77
	v_add_f32_e32 v68, v90, v68
	v_add_f32_e32 v69, v91, v69
	v_mfma_f32_32x32x16_bf16 v[32:47], v[136:139], v[64:67], v[32:47]
	v_add_f32_e64 v68, v70, v68
	v_add_f32_e64 v69, v71, v69
	v_add_f32_e64 v68, v92, v68
	v_add_f32_e64 v69, v93, v69
	v_add_f32_e64 v68, v74, v68
	v_add_f32_e64 v69, v75, v69
	v_add_f32_e32 v68, v80, v68
	v_add_f32_e32 v69, v81, v69
	v_mfma_f32_32x32x16_bf16 v[16:31], v[10:13], v[64:67], v[16:31]
	v_add_f32_e64 v68, v76, v68
	v_add_f32_e64 v69, v77, v69
	v_add_f32_e32 v68, v68, v69
	v_add_f32_e32 v218, v218, v68

; __device__ __forceinline__ unsigned cvtpk(float lo, float hi) { const f32x2 v = {lo, hi}; const bf16x2_t b = __builtin_convertvector(v, bf16x2_t); return __builtin_bit_cast(unsigned, b); }
; __device__ __forceinline__ void sm_pv(f32x16& s0, f32x16& s1, f32x16& o0, f32x16& o1, float& m_run, float& l_run, f32x16& negm, LAS unsigned char* vb, bool domask, int kbase, int qm, int r32, int hi) {
;     ...
;     f32x2 ps2 = (f32x2){0.f, 0.f};
; #pragma unroll
;     for (int r = 0; r < 16; r += 2) { s0[r] = __builtin_amdgcn_exp2f(s0[r]); s0[r + 1] = __builtin_amdgcn_exp2f(s0[r + 1]); s1[r] = __builtin_amdgcn_exp2f(s1[r]); s1[r + 1] = __builtin_amdgcn_exp2f(s1[r + 1]);
;         ps2 += (f32x2){s0[r], s0[r + 1]}; ps2 += (f32x2){s1[r], s1[r + 1]}; }
;     l_run += ps2[0] + ps2[1];
;     u32x4 pw[4];
; #pragma unroll
;     for (int i = 0; i < 4; ++i) { pw[0][i] = cvtpk(s0[2 * i], s0[2 * i + 1]); pw[1][i] = cvtpk(s0[8 + 2 * i], s0[8 + 2 * i + 1]); pw[2][i] = cvtpk(s1[2 * i], s1[2 * i + 1]); pw[3][i] = cvtpk(s1[8 + 2 * i], s1[8 + 2 * i + 1]); }
; #pragma unroll
;     for (int kk = 0; kk < 4; ++kk) {
;         const bf16x8 pf = __builtin_bit_cast(bf16x8, pw[kk]);
;         { const s16x4 lo = vlo[2 * kk], hh = vhh[2 * kk];
;           const bf16x8 vf = (bf16x8){lo[0], lo[1], lo[2], lo[3], hh[0], hh[1], hh[2], hh[3]};
;           o0 = __builtin_amdgcn_mfma_f32_32x32x16_bf16(vf, pf, o0, 0, 0, 0); }
;         { const s16x4 lo = vlo[2 * kk + 1], hh = vhh[2 * kk + 1];
;           const bf16x8 vf = (bf16x8){lo[0], lo[1], lo[2], lo[3], hh[0], hh[1], hh[2], hh[3]};
;           o1 = __builtin_amdgcn_mfma_f32_32x32x16_bf16(vf, pf, o1, 0, 0, 0); }
;     }
.LBB0_450:
	v_exp_f32_e32 v80, v80
	v_exp_f32_e32 v81, v81
	v_exp_f32_e32 v160, v82
	v_exp_f32_e32 v161, v83
	v_exp_f32_e32 v84, v84
	v_exp_f32_e32 v85, v85
	v_exp_f32_e32 v86, v86
	v_exp_f32_e32 v87, v87
	v_exp_f32_e32 v156, v64
	v_exp_f32_e32 v157, v65
	v_add_f32_e32 v64, 0, v80
	v_add_f32_e32 v65, 0, v81
	v_cvt_pk_bf16_f32 v80, v80, v81
	v_cvt_pk_bf16_f32 v81, v160, v161
	v_cvt_pk_bf16_f32 v82, v84, v85
	v_cvt_pk_bf16_f32 v83, v86, v87
	v_exp_f32_e32 v88, v88
	v_exp_f32_e32 v89, v89
	s_waitcnt lgkmcnt(0)
	v_mfma_f32_32x32x16_bf16 v[32:47], v[152:155], v[80:83], v[32:47]
	v_exp_f32_e32 v90, v90
	v_exp_f32_e32 v91, v91
	v_exp_f32_e32 v92, v92
	v_exp_f32_e32 v93, v93
	v_add_f32_e32 v158, v156, v64
	v_add_f32_e32 v159, v157, v65
	v_exp_f32_e32 v162, v66
	v_exp_f32_e32 v163, v67
	v_mfma_f32_32x32x16_bf16 v[16:31], v[148:151], v[80:83], v[16:31]
	v_exp_f32_e32 v80, v94
	v_exp_f32_e32 v81, v95
	v_cvt_pk_bf16_f32 v64, v88, v89
	v_cvt_pk_bf16_f32 v65, v90, v91
	v_cvt_pk_bf16_f32 v66, v92, v93
	v_cvt_pk_bf16_f32 v67, v80, v81
	v_exp_f32_e32 v68, v68
	v_exp_f32_e32 v69, v69
	v_mfma_f32_32x32x16_bf16 v[32:47], v[144:147], v[64:67], v[32:47]
	v_exp_f32_e32 v70, v70
	v_exp_f32_e32 v71, v71
	v_add_f32_e32 v82, v160, v158
	v_add_f32_e32 v83, v161, v159
	v_exp_f32_e32 v72, v72
	v_add_f32_e32 v82, v162, v82
	v_add_f32_e32 v83, v163, v83
	v_exp_f32_e32 v73, v73
	v_add_f32_e32 v82, v84, v82
	v_add_f32_e32 v83, v85, v83
	v_mfma_f32_32x32x16_bf16 v[16:31], v[140:143], v[64:67], v[16:31]
	v_cvt_pk_bf16_f32 v64, v156, v157
	v_cvt_pk_bf16_f32 v65, v162, v163
	v_cvt_pk_bf16_f32 v66, v68, v69
	v_cvt_pk_bf16_f32 v67, v70, v71
	v_add_f32_e64 v82, v68, v82
	v_add_f32_e64 v83, v69, v83
	v_add_f32_e32 v82, v86, v82
	v_add_f32_e32 v83, v87, v83
	v_mfma_f32_32x32x16_bf16 v[32:47], v[136:139], v[64:67], v[32:47]
	v_add_f32_e64 v68, v70, v82
	v_add_f32_e64 v69, v71, v83
	v_exp_f32_e32 v70, v74
	v_exp_f32_e32 v71, v75
	v_exp_f32_e32 v74, v76
	v_exp_f32_e32 v75, v77
	v_add_f32_e32 v68, v88, v68
	v_add_f32_e32 v69, v89, v69
	v_mfma_f32_32x32x16_bf16 v[16:31], v[10:13], v[64:67], v[16:31]
	v_exp_f32_e32 v64, v78
	v_exp_f32_e32 v65, v79
	v_add_f32_e32 v68, v72, v68
	v_add_f32_e32 v69, v73, v69
	v_cvt_pk_bf16_f32 v10, v72, v73
	v_add_f32_e32 v68, v90, v68
	v_add_f32_e32 v69, v91, v69
	v_cvt_pk_bf16_f32 v11, v70, v71
	v_cvt_pk_bf16_f32 v12, v74, v75
	v_cvt_pk_bf16_f32 v13, v64, v65
	s_nop 0
	v_mfma_f32_32x32x16_bf16 v[32:47], v[6:9], v[10:13], v[32:47]
	v_add_f32_e64 v6, v70, v68
	v_add_f32_e64 v7, v71, v69
	v_add_f32_e64 v6, v92, v6
	v_add_f32_e64 v7, v93, v7
	v_add_f32_e64 v6, v74, v6
	v_add_f32_e64 v7, v75, v7
	v_add_f32_e32 v6, v80, v6
	v_add_f32_e32 v7, v81, v7
	v_mfma_f32_32x32x16_bf16 v[16:31], v[2:5], v[10:13], v[16:31]
	v_add_f32_e64 v6, v64, v6
	v_add_f32_e64 v7, v65, v7
	v_add_f32_e32 v6, v6, v7
	v_add_f32_e32 v218, v218, v6

; __device__ __forceinline__ unsigned cvtpk(float lo, float hi) { const f32x2 v = {lo, hi}; const bf16x2_t b = __builtin_convertvector(v, bf16x2_t); return __builtin_bit_cast(unsigned, b); }
; __device__ __forceinline__ void sm_pv(f32x16& s0, f32x16& s1, f32x16& o0, f32x16& o1, float& m_run, float& l_run, f32x16& negm, LAS unsigned char* vb, bool domask, int kbase, int qm, int r32, int hi) {
;     ...
;     f32x2 ps2 = (f32x2){0.f, 0.f};
; #pragma unroll
;     for (int r = 0; r < 16; r += 2) { s0[r] = __builtin_amdgcn_exp2f(s0[r]); s0[r + 1] = __builtin_amdgcn_exp2f(s0[r + 1]); s1[r] = __builtin_amdgcn_exp2f(s1[r]); s1[r + 1] = __builtin_amdgcn_exp2f(s1[r + 1]);
;         ps2 += (f32x2){s0[r], s0[r + 1]}; ps2 += (f32x2){s1[r], s1[r + 1]}; }
;     l_run += ps2[0] + ps2[1];
;     u32x4 pw[4];
; #pragma unroll
;     for (int i = 0; i < 4; ++i) { pw[0][i] = cvtpk(s0[2 * i], s0[2 * i + 1]); pw[1][i] = cvtpk(s0[8 + 2 * i], s0[8 + 2 * i + 1]); pw[2][i] = cvtpk(s1[2 * i], s1[2 * i + 1]); pw[3][i] = cvtpk(s1[8 + 2 * i], s1[8 + 2 * i + 1]); }
; #pragma unroll
;     for (int kk = 0; kk < 4; ++kk) {
;         const bf16x8 pf = __builtin_bit_cast(bf16x8, pw[kk]);
;         { const s16x4 lo = vlo[2 * kk], hh = vhh[2 * kk];
;           const bf16x8 vf = (bf16x8){lo[0], lo[1], lo[2], lo[3], hh[0], hh[1], hh[2], hh[3]};
;           o0 = __builtin_amdgcn_mfma_f32_32x32x16_bf16(vf, pf, o0, 0, 0, 0); }
;         { const s16x4 lo = vlo[2 * kk + 1], hh = vhh[2 * kk + 1];
;           const bf16x8 vf = (bf16x8){lo[0], lo[1], lo[2], lo[3], hh[0], hh[1], hh[2], hh[3]};
;           o1 = __builtin_amdgcn_mfma_f32_32x32x16_bf16(vf, pf, o1, 0, 0, 0); }
;     }
.LBB0_461:
	v_exp_f32_e32 v14, v80
	v_exp_f32_e32 v15, v81
	v_exp_f32_e32 v160, v82
	v_exp_f32_e32 v161, v83
	v_exp_f32_e32 v84, v84
	v_exp_f32_e32 v85, v85
	v_exp_f32_e32 v86, v86
	v_exp_f32_e32 v87, v87
	v_cvt_pk_bf16_f32 v80, v14, v15
	v_cvt_pk_bf16_f32 v81, v160, v161
	v_cvt_pk_bf16_f32 v82, v84, v85
	v_cvt_pk_bf16_f32 v83, v86, v87
	v_exp_f32_e32 v156, v64
	v_exp_f32_e32 v157, v65
	s_waitcnt lgkmcnt(0)
	v_mfma_f32_32x32x16_bf16 v[32:47], v[152:155], v[80:83], v[32:47]
	v_exp_f32_e32 v88, v88
	v_exp_f32_e32 v89, v89
	v_exp_f32_e32 v90, v90
	v_exp_f32_e32 v91, v91
	v_exp_f32_e32 v92, v92
	v_exp_f32_e32 v93, v93
	v_add_f32_e32 v64, 0, v14
	v_add_f32_e32 v65, 0, v15
	v_mfma_f32_32x32x16_bf16 v[16:31], v[148:151], v[80:83], v[16:31]
	v_exp_f32_e32 v80, v94
	v_exp_f32_e32 v81, v95
	v_add_f32_e32 v158, v156, v64
	v_add_f32_e32 v159, v157, v65
	v_exp_f32_e32 v162, v66
	v_exp_f32_e32 v163, v67
	v_cvt_pk_bf16_f32 v64, v88, v89
	v_cvt_pk_bf16_f32 v65, v90, v91
	v_cvt_pk_bf16_f32 v66, v92, v93
	v_cvt_pk_bf16_f32 v67, v80, v81
	v_exp_f32_e32 v14, v68
	v_exp_f32_e32 v15, v69
	v_mfma_f32_32x32x16_bf16 v[32:47], v[144:147], v[64:67], v[32:47]
	v_exp_f32_e32 v70, v70
	v_exp_f32_e32 v71, v71
	v_add_f32_e32 v68, v160, v158
	v_add_f32_e32 v69, v161, v159
	v_exp_f32_e32 v72, v72
	v_add_f32_e32 v68, v162, v68
	v_add_f32_e32 v69, v163, v69
	v_exp_f32_e32 v73, v73
	v_add_f32_e32 v68, v84, v68
	v_add_f32_e32 v69, v85, v69
	v_mfma_f32_32x32x16_bf16 v[16:31], v[140:143], v[64:67], v[16:31]
	v_cvt_pk_bf16_f32 v64, v156, v157
	v_cvt_pk_bf16_f32 v65, v162, v163
	v_cvt_pk_bf16_f32 v66, v14, v15
	v_cvt_pk_bf16_f32 v67, v70, v71
	v_add_f32_e64 v68, v14, v68
	v_add_f32_e64 v69, v15, v69
	v_add_f32_e32 v68, v86, v68
	v_add_f32_e32 v69, v87, v69
	v_mfma_f32_32x32x16_bf16 v[32:47], v[136:139], v[64:67], v[32:47]
	v_add_f32_e64 v14, v70, v68
	v_add_f32_e64 v15, v71, v69
	v_exp_f32_e32 v68, v74
	v_exp_f32_e32 v69, v75
	v_exp_f32_e32 v70, v76
	v_exp_f32_e32 v71, v77
	v_add_f32_e32 v14, v88, v14
	v_add_f32_e32 v15, v89, v15
	v_mfma_f32_32x32x16_bf16 v[16:31], v[10:13], v[64:67], v[16:31]
	v_exp_f32_e32 v64, v78
	v_exp_f32_e32 v65, v79
	v_add_f32_e32 v14, v72, v14
	v_add_f32_e32 v15, v73, v15
	v_cvt_pk_bf16_f32 v10, v72, v73
	v_cvt_pk_bf16_f32 v11, v68, v69
	v_cvt_pk_bf16_f32 v12, v70, v71
	v_cvt_pk_bf16_f32 v13, v64, v65
	v_add_f32_e32 v14, v90, v14
	v_add_f32_e32 v15, v91, v15
	v_mfma_f32_32x32x16_bf16 v[32:47], v[6:9], v[10:13], v[32:47]
	v_add_f32_e64 v6, v68, v14
	v_add_f32_e64 v7, v69, v15
	v_add_f32_e64 v6, v92, v6
	v_add_f32_e64 v7, v93, v7
	v_add_f32_e64 v6, v70, v6
	v_add_f32_e64 v7, v71, v7
	v_add_f32_e32 v6, v80, v6
	v_add_f32_e32 v7, v81, v7
	v_mfma_f32_32x32x16_bf16 v[16:31], v[2:5], v[10:13], v[16:31]
	v_add_f32_e64 v6, v64, v6
	v_add_f32_e64 v7, v65, v7
	v_add_f32_e32 v6, v6, v7
	v_add_f32_e32 v218, v218, v6

; template <class Epi, class Sched, bool ALIGN_EPI = false, bool SP2 = false>
; __device__ __forceinline__ void gemm_phase(PG8_LAS unsigned char* lds, const Gemm g, const Sched& S, const Epi& E, int wid0) {
;     ...
;         const char* nA = has_next ? PG8_APTR(nxt) : cA; const char* nB = has_next ? (const char*)g.Bt + (size_t)nxt.pn * tstepB : cB;
;         for (int t = 0; t < nt; t += 2) {
;             const bool last = (t == nt - 2);
;             const char* a1 = cA + (size_t)(t + 1) * kstep;
;             const char* a2 = last ? nA : cA + (size_t)(t + 2) * kstep; const char* b2 = last ? nB : cB + (size_t)(t + 2) * kstep;
;             const char* a3 = a2 + kstep; const char* b3 = b2 + kstep;
;     ...
; #pragma unroll
;         for (int a = 0; a < 2; ++a)
; #pragma unroll
;             for (int b = 0; b < 2; ++b)
; #pragma unroll
;                 for (int m = 0; m < 4; ++m)
; #pragma unroll
;                     for (int n = 0; n < 2; ++n) acc[a][b][m][n] = (f32x4){0.f, 0.f, 0.f, 0.f};
.LBB0_555:
	s_ashr_i32 s45, s44, 31
	s_lshl_b64 s[48:49], s[44:45], 19
	s_add_u32 s48, s23, s48
	s_addc_u32 s49, s16, s49
	s_and_b64 s[4:5], s[4:5], exec
	s_cselect_b32 s45, s49, s47
	s_cselect_b32 vcc_lo, s48, s46
	s_add_u32 s4, s14, 0x40080
	s_addc_u32 s5, s15, 0
	s_add_u32 s46, s46, 0x100
	v_mov_b32_e32 v38, 0
	s_addc_u32 s47, s47, 0
	s_mov_b32 vcc_hi, -2
	v_mov_b32_e32 v39, v38
	v_mov_b64_e32 v[2:3], v[38:39]
	v_mov_b64_e32 v[4:5], v[38:39]
	v_mov_b64_e32 v[6:7], v[38:39]
	v_mov_b64_e32 v[8:9], v[38:39]
	v_mov_b64_e32 v[10:11], v[38:39]
	v_mov_b64_e32 v[12:13], v[38:39]
	v_mov_b64_e32 v[14:15], v[38:39]
	v_mov_b64_e32 v[16:17], v[38:39]
	v_mov_b64_e32 v[18:19], v[38:39]
	v_mov_b64_e32 v[20:21], v[38:39]
	v_mov_b64_e32 v[22:23], v[38:39]
	v_mov_b64_e32 v[24:25], v[38:39]
	v_mov_b64_e32 v[26:27], v[38:39]
	v_mov_b64_e32 v[28:29], v[38:39]
	v_mov_b64_e32 v[30:31], v[38:39]
	v_mov_b64_e32 v[32:33], v[38:39]
	v_mov_b64_e32 v[34:35], v[38:39]
	v_mov_b64_e32 v[36:37], v[38:39]
	v_mov_b64_e32 v[40:41], v[38:39]
	v_mov_b64_e32 v[42:43], v[38:39]
	v_mov_b64_e32 v[44:45], v[38:39]
	v_mov_b64_e32 v[46:47], v[38:39]
	v_mov_b64_e32 v[48:49], v[38:39]
	v_mov_b64_e32 v[50:51], v[38:39]
	v_mov_b64_e32 v[52:53], v[38:39]
	v_mov_b64_e32 v[54:55], v[38:39]
	v_mov_b64_e32 v[56:57], v[38:39]
	v_mov_b64_e32 v[58:59], v[38:39]
	v_mov_b64_e32 v[60:61], v[38:39]
	v_mov_b64_e32 v[62:63], v[38:39]
	v_mov_b64_e32 v[64:65], v[38:39]
	v_mov_b64_e32 v[66:67], v[38:39]
	v_mov_b64_e32 v[68:69], v[38:39]
	v_mov_b64_e32 v[70:71], v[38:39]
	v_mov_b64_e32 v[72:73], v[38:39]
	v_mov_b64_e32 v[74:75], v[38:39]
	v_mov_b64_e32 v[76:77], v[38:39]
	v_mov_b64_e32 v[78:79], v[38:39]
	v_mov_b64_e32 v[80:81], v[38:39]
	v_mov_b64_e32 v[82:83], v[38:39]
	v_mov_b64_e32 v[84:85], v[38:39]
	v_mov_b64_e32 v[86:87], v[38:39]
	v_mov_b64_e32 v[88:89], v[38:39]
	v_mov_b64_e32 v[90:91], v[38:39]
	v_mov_b64_e32 v[92:93], v[38:39]
	v_mov_b64_e32 v[94:95], v[38:39]
	v_mov_b64_e32 v[96:97], v[38:39]
	v_mov_b64_e32 v[98:99], v[38:39]
	v_mov_b64_e32 v[100:101], v[38:39]
	v_mov_b64_e32 v[106:107], v[38:39]
	v_mov_b64_e32 v[108:109], v[38:39]
	v_mov_b64_e32 v[110:111], v[38:39]
	v_mov_b64_e32 v[112:113], v[38:39]
	v_mov_b64_e32 v[114:115], v[38:39]
	v_mov_b64_e32 v[116:117], v[38:39]
	v_mov_b64_e32 v[118:119], v[38:39]
	v_mov_b64_e32 v[120:121], v[38:39]
	v_mov_b64_e32 v[122:123], v[38:39]
	v_mov_b64_e32 v[124:125], v[38:39]
	v_mov_b64_e32 v[126:127], v[38:39]
	v_mov_b64_e32 v[128:129], v[38:39]
	v_mov_b64_e32 v[130:131], v[38:39]
	v_mov_b64_e32 v[132:133], v[38:39]

; #define PG8_LAS __attribute__((address_space(3)))
;     static __device__ __forceinline__ int xi(int wr, int wc, int ai, int s, int bj, int n, int fq) { return (((((wr * 4 + wc) * 2 + ai) * 2 + s) * 2 + bj) * 2 + n) * 4 + fq; }
;     __device__ __forceinline__ void run(f32x4 (&acc)[2][2][4][2], const Unit& u, int wr, int wc, int fr_, int fq_, int par) const {
;     ...
;             for (int m = 0; m < 4; ++m) { const float sc = rsl[ai * HALF + wr * 64 + 4 * fr + m];
; #pragma unroll
;                 for (int bj = 0; bj < 2; ++bj)
; #pragma unroll
;                     for (int n = 0; n < 2; ++n) acc[ai][bj][m][n] = acc[ai][bj][m][n] * sc; }
;         if (fr == 15) {
; #pragma unroll
;             for (int ai = 0; ai < 2; ++ai)
; #pragma unroll
;                 for (int bj = 0; bj < 2; ++bj)
; #pragma unroll
;                     for (int n = 0; n < 2; ++n) { xch[xi(wr, wc, ai, 0, bj, n, fq)] = acc[ai][bj][2][n]; xch[xi(wr, wc, ai, 1, bj, n, fq)] = acc[ai][bj][3][n]; }
;         }
;         asm volatile("s_waitcnt lgkmcnt(0)" ::: "memory"); __builtin_amdgcn_s_barrier(); asm volatile("" ::: "memory");
;         const int src = (lane & 48) | ((fr + 15) & 15);
;         const f32x4 z4 = (f32x4){0.f, 0.f, 0.f, 0.f};
;         const PG8_LAS float* wlane = wl + wc * 32 + 8 * fq;
;         const int cu = u.pn * 128 + wc * 32;
; #pragma unroll
;         for (int ai = 0; ai < 2; ++ai) {
;             const bool has_prev = (wr | ai) != 0;
;             const int swr = wr ^ 1, sai = wr ? ai : 0;
;             const int growu = a_row0 + u.pm * a_rstep + ai * HALF + wr * 64;
;             const int grow0 = growu + 4 * fr;
;             const int tz = ((grow0 % seqlen) + seqlen) % seqlen;
;     ...
;             if (__builtin_amdgcn_ballot_w64(tz < 2 || tz + 3 >= seqlen) != 0ull) PG8_CONV_RUN(true); else PG8_CONV_RUN(false);
.LBB0_561:
	s_or_b64 exec, exec, s[4:5]
	s_lshl_b32 s4, s14, 12
	s_mul_i32 s14, s58, 0xfe
	v_lshlrev_b32_e32 v251, 2, v253
	s_add_i32 s15, s0, s14
	v_add_u32_e32 v252, s15, v251
	v_pk_mul_f32 v[210:211], v[94:95], v[134:135] op_sel:[0,1]
	v_mul_hi_i32 v94, v252, s62
	s_add_i32 s4, s91, s4
	v_lshrrev_b32_e32 v95, 31, v94
	v_ashrrev_i32_e32 v94, 7, v94
	v_lshl_add_u32 v249, v250, 5, s4
	v_add_u32_e32 v94, v94, v95
	s_movk_i32 s4, 0x810
	v_mul_lo_u32 v94, v94, s4
	v_sub_u32_e32 v94, v252, v94
	v_add_u32_e32 v95, 0x810, v94
	v_cmp_gt_i32_e32 vcc, 0, v94
	s_waitcnt lgkmcnt(0)
	s_barrier
	s_movk_i32 s4, 0xf7f5
	v_cndmask_b32_e32 v254, v94, v95, vcc
	v_add_u32_e32 v94, 0xfffff7f3, v254
	v_pk_mul_f32 v[214:215], v[130:131], v[134:135] op_sel_hi:[1,0]
	v_pk_mul_f32 v[216:217], v[132:133], v[134:135] op_sel_hi:[1,0]
	v_pk_mul_f32 v[222:223], v[126:127], v[134:135] op_sel_hi:[1,0]
	v_pk_mul_f32 v[224:225], v[128:129], v[134:135] op_sel_hi:[1,0]
	v_pk_mul_f32 v[230:231], v[114:115], v[134:135] op_sel_hi:[1,0]
	v_pk_mul_f32 v[232:233], v[116:117], v[134:135] op_sel_hi:[1,0]
	v_pk_mul_f32 v[68:69], v[110:111], v[134:135] op_sel_hi:[1,0]
	v_pk_mul_f32 v[208:209], v[112:113], v[134:135] op_sel_hi:[1,0]
	v_pk_mul_f32 v[218:219], v[122:123], v[134:135] op_sel:[0,1]
	v_pk_mul_f32 v[220:221], v[124:125], v[134:135] op_sel:[0,1]
	v_pk_mul_f32 v[226:227], v[118:119], v[134:135] op_sel:[0,1]
	v_pk_mul_f32 v[228:229], v[120:121], v[134:135] op_sel:[0,1]
	v_pk_mul_f32 v[234:235], v[98:99], v[134:135] op_sel:[0,1]
	v_pk_mul_f32 v[236:237], v[100:101], v[134:135] op_sel:[0,1]
	v_pk_mul_f32 v[212:213], v[96:97], v[134:135] op_sel:[0,1]
	v_cmp_gt_u32_e32 vcc, s4, v94
	s_cbranch_vccz .LBB0_579
	v_mov_b32_e32 v150, 0
	s_and_b64 vcc, exec, s[36:37]
	v_mov_b32_e32 v134, 0
	v_mov_b32_e32 v135, 0
	v_mov_b32_e32 v136, 0
	v_mov_b32_e32 v137, 0
	s_cbranch_vccz .LBB0_564
	v_lshl_add_u32 v94, v250, 4, s57
	ds_read_b128 v[134:137], v94

.LBB0_566:
	ds_read_b128 v[142:145], v249
	ds_read_b128 v[126:129], v249 offset:1024
	ds_read_b128 v[118:121], v249 offset:2048
	ds_read_b128 v[154:157], v249 offset:3072
	s_waitcnt lgkmcnt(4)
	v_mov_b32_dpp v134, v78 row_shr:1 row_mask:0xf bank_mask:0xf
	v_mov_b32_dpp v150, v82 row_shr:1 row_mask:0xf bank_mask:0xf
	v_mov_b32_dpp v135, v79 row_shr:1 row_mask:0xf bank_mask:0xf
	v_mov_b32_dpp v151, v83 row_shr:1 row_mask:0xf bank_mask:0xf
	v_mov_b32_dpp v136, v80 row_shr:1 row_mask:0xf bank_mask:0xf
	v_mov_b32_dpp v152, v84 row_shr:1 row_mask:0xf bank_mask:0xf
	v_mov_b32_dpp v137, v81 row_shr:1 row_mask:0xf bank_mask:0xf
	v_mov_b32_dpp v153, v85 row_shr:1 row_mask:0xf bank_mask:0xf
	v_mov_b32_e32 v130, 0
	s_and_b64 vcc, exec, s[4:5]
	v_mov_b32_e32 v114, 0
	v_mov_b32_e32 v115, 0
	v_mov_b32_e32 v116, 0
	v_mov_b32_e32 v117, 0
	s_cbranch_vccnz .LBB0_568
	v_lshl_add_u32 v94, v250, 4, s57
	ds_read_b128 v[114:117], v94 offset:64

.LBB0_570:
	ds_read_b128 v[162:165], v249 offset:16
	ds_read_b128 v[158:161], v249 offset:1040
	ds_read_b128 v[98:101], v249 offset:2064
	ds_read_b128 v[182:185], v249 offset:3088
	s_waitcnt lgkmcnt(4)
	v_mov_b32_dpp v114, v86 row_shr:1 row_mask:0xf bank_mask:0xf
	v_mov_b32_dpp v130, v90 row_shr:1 row_mask:0xf bank_mask:0xf
	v_mov_b32_dpp v115, v87 row_shr:1 row_mask:0xf bank_mask:0xf
	v_mov_b32_dpp v131, v91 row_shr:1 row_mask:0xf bank_mask:0xf
	v_mov_b32_dpp v116, v88 row_shr:1 row_mask:0xf bank_mask:0xf
	v_mov_b32_dpp v132, v92 row_shr:1 row_mask:0xf bank_mask:0xf
	v_mov_b32_dpp v117, v89 row_shr:1 row_mask:0xf bank_mask:0xf
	v_mov_b32_dpp v133, v93 row_shr:1 row_mask:0xf bank_mask:0xf
	v_mov_b32_e32 v122, 0
	s_and_b64 vcc, exec, s[4:5]
	v_mov_b32_e32 v110, 0
	v_mov_b32_e32 v111, 0
	v_mov_b32_e32 v112, 0
	v_mov_b32_e32 v113, 0
	s_cbranch_vccnz .LBB0_572
	v_lshl_add_u32 v110, v250, 4, s57
	ds_read_b128 v[110:113], v110 offset:128

.LBB0_574:
	ds_read_b128 v[194:197], v249 offset:512
	ds_read_b128 v[146:149], v249 offset:1536
	ds_read_b128 v[94:97], v249 offset:2560
	ds_read_b128 v[198:201], v249 offset:3584
	s_waitcnt lgkmcnt(4)
	v_mov_b32_dpp v110, v102 row_shr:1 row_mask:0xf bank_mask:0xf
	v_mov_b32_dpp v122, v106 row_shr:1 row_mask:0xf bank_mask:0xf
	v_mov_b32_dpp v111, v103 row_shr:1 row_mask:0xf bank_mask:0xf
	v_mov_b32_dpp v123, v107 row_shr:1 row_mask:0xf bank_mask:0xf
	v_mov_b32_dpp v112, v104 row_shr:1 row_mask:0xf bank_mask:0xf
	v_mov_b32_dpp v124, v108 row_shr:1 row_mask:0xf bank_mask:0xf
	v_mov_b32_dpp v113, v105 row_shr:1 row_mask:0xf bank_mask:0xf
	v_mov_b32_dpp v125, v109 row_shr:1 row_mask:0xf bank_mask:0xf
	ds_read_b128 v[174:177], v249 offset:528
	ds_read_b128 v[170:173], v249 offset:1552
	ds_read_b128 v[166:169], v249 offset:2576
	ds_read_b128 v[178:181], v249 offset:3600
	v_mov_b32_e32 v190, 0
	s_and_b64 vcc, exec, s[4:5]
	v_mov_b32_e32 v186, 0
	v_mov_b32_e32 v187, 0
	v_mov_b32_e32 v188, 0
	v_mov_b32_e32 v189, 0
	s_cbranch_vccnz .LBB0_576
	v_lshl_add_u32 v138, v250, 4, s57
	ds_read_b128 v[186:189], v138 offset:192
